# MLA loop: hoisted LDS store addresses, interleaved row-sum chains, batched sub/exp; lazy softmax rescale (threshold 8) in MLA loop
# speedup vs baseline: 1.0550x; 1.0142x over previous
.LBB0_744:
	s_and_b64 vcc, exec, s[0:1]
	s_cbranch_vccz .LBB0_739
	s_lshl_b32 s0, s5, 8
	v_mov_b32_e32 v29, v193
	s_and_b32 s0, s0, 0x700
	s_ashr_i32 s3, s5, 6
	v_and_b32_e32 v0, 0xffffffc0, v29
	v_and_b32_e32 v30, 31, v29
	v_add_u32_e32 v0, s0, v0
	s_bfe_u32 s8, s5, 0x30003
	s_lshl_b32 s1, s3, 3
	v_or_b32_e32 v188, v0, v30
	s_or_b32 s13, s1, s8
	v_ashrrev_i32_e32 v189, 31, v188
	v_mad_i64_i32 v[2:3], s[0:1], s13, v198, v[188:189]
	v_mov_b64_e32 v[4:5], s[40:41]
	s_movk_i32 s6, 0xc0
	v_bfe_u32 v31, v29, 5, 1
	v_mad_u64_u32 v[4:5], s[0:1], v2, s6, v[4:5]
	v_lshlrev_b32_e32 v0, 4, v31
	v_mad_i32_i24 v5, v3, s6, v5
	v_lshl_add_u64 v[26:27], v[4:5], 0, v[0:1]
	s_mov_b64 s[0:1], 0x1800
	v_lshl_add_u64 v[22:23], v[26:27], 0, s[0:1]
	s_movk_i32 s0, 0x1000
	v_add_co_u32_e32 v2, vcc, s0, v26
	s_nop 1
	v_addc_co_u32_e32 v3, vcc, 0, v27, vcc
	s_barrier
	global_load_dwordx4 v[2:5], v[2:3], off offset:2048
	s_nop 0
	global_load_dwordx4 v[6:9], v[22:23], off offset:32
	global_load_dwordx4 v[10:13], v[22:23], off offset:64
	global_load_dwordx4 v[14:17], v[22:23], off offset:96
	global_load_dwordx4 v[18:21], v[22:23], off offset:128
	s_nop 0
	global_load_dwordx4 v[22:25], v[22:23], off offset:160
	v_lshrrev_b32_e32 v29, 1, v29
	s_mov_b32 s0, 0xfffffe0
	v_and_or_b32 v29, v29, s0, v30
	s_mul_i32 s9, s13, 0x6c000
	v_add_u32_e32 v192, 0, v0
	v_readlane_b32 s0, v254, 7
	s_movk_i32 s16, 0xd0
	s_add_u32 s6, s0, s9
	v_mad_u64_u32 v[194:195], s[0:1], v29, s16, v[192:193]
	s_mul_hi_i32 s10, s13, 0x6c000
	v_readlane_b32 s0, v254, 8
	v_mov_b32_e32 v28, v193
	s_mul_hi_i32 s12, s13, 0x48000
	s_mul_i32 s13, s13, 0x48000
	s_addc_u32 s7, s0, s10
	v_readlane_b32 s0, v254, 9
	s_add_u32 s0, s0, s13
	v_readlane_b32 s1, v254, 10
	global_load_dwordx4 v[144:147], v[26:27], off
	global_load_dwordx4 v[148:151], v[26:27], off offset:32
	global_load_dwordx4 v[152:155], v[26:27], off offset:64
	global_load_dwordx4 v[156:159], v[26:27], off offset:96
	global_load_dwordx4 v[160:163], v[26:27], off offset:128
	global_load_dwordx4 v[164:167], v[26:27], off offset:160
	s_addc_u32 s1, s1, s12
	s_movk_i32 s17, 0x2000
	s_movk_i32 s11, 0x1200
	v_lshlrev_b32_e32 v190, 3, v31
	v_mul_u32_u24_e32 v191, 0xd0, v30
	v_mov_b32_e32 v215, 0xf149f2ca
	v_mov_b32_e32 v195, 0
	s_waitcnt vmcnt(11)
	ds_write_b128 v194, v[2:5] offset:47104
	s_waitcnt vmcnt(10)
	ds_write_b128 v194, v[6:9] offset:47136
	s_waitcnt vmcnt(9)
	ds_write_b128 v194, v[10:13] offset:47168
	s_waitcnt vmcnt(8)
	ds_write_b128 v194, v[14:17] offset:47200
	s_waitcnt vmcnt(7)
	ds_write_b128 v194, v[18:21] offset:47232
	s_waitcnt vmcnt(6)
	ds_write_b128 v194, v[22:25] offset:47264
	v_mov_b32_e32 v23, v193
	v_ashrrev_i32_e32 v29, 31, v28
	v_lshlrev_b32_e32 v0, 4, v28
	v_add_u32_e32 v2, 0x100, v28
	v_lshl_add_u64 v[4:5], v[28:29], 4, s[6:7]
	v_and_b32_e32 v0, 0x70, v0
	v_ashrrev_i32_e32 v14, 3, v28
	v_ashrrev_i32_e32 v3, 31, v2
	v_ashrrev_i32_e32 v16, 3, v2
	v_add_co_u32_e32 v10, vcc, s17, v4
	v_lshl_add_u64 v[12:13], s[0:1], 0, v[0:1]
	v_lshl_add_u64 v[6:7], v[2:3], 4, s[6:7]
	v_addc_co_u32_e32 v11, vcc, 0, v5, vcc
	v_mad_i64_i32 v[14:15], s[14:15], v14, s11, v[12:13]
	v_mad_i64_i32 v[18:19], s[14:15], v16, s11, v[12:13]
	global_load_dwordx4 v[2:5], v[4:5], off
	s_nop 0
	global_load_dwordx4 v[6:9], v[6:7], off
	s_nop 0
	global_load_dwordx4 v[10:13], v[10:11], off
	s_nop 0
	global_load_dwordx4 v[14:17], v[14:15], off
	s_nop 0
	global_load_dwordx4 v[18:21], v[18:19], off
	s_mov_b32 s14, 0x2aaaaaab
	v_mov_b32_e32 v22, v193
	v_mul_hi_i32 v0, v23, s14
	v_add_u32_e32 v28, 0x100, v23
	v_add_u32_e32 v29, 0x200, v23
	v_lshlrev_b32_e32 v24, 4, v23
	v_lshrrev_b32_e32 v26, 31, v0
	v_ashrrev_i32_e32 v0, 1, v0
	v_mul_hi_i32 v27, v28, s14
	v_mul_hi_i32 v32, v29, s14
	v_and_b32_e32 v24, 0x70, v24
	v_add_u32_e32 v26, v0, v26
	v_lshrrev_b32_e32 v34, 31, v27
	v_ashrrev_i32_e32 v27, 1, v27
	v_lshrrev_b32_e32 v25, 3, v23
	v_lshrrev_b32_e32 v33, 3, v28
	v_lshrrev_b32_e32 v35, 31, v32
	v_ashrrev_i32_e32 v32, 1, v32
	v_add_u32_e32 v0, 0, v24
	v_mul_lo_u32 v36, v26, 12
	v_add_u32_e32 v34, v27, v34
	v_mul_lo_u32 v37, v26, s16
	v_add_u32_e32 v32, v32, v35
	v_mad_u64_u32 v[24:25], s[14:15], v25, s91, v[0:1]
	v_mad_u64_u32 v[26:27], s[14:15], v33, s91, v[0:1]
	v_sub_u32_e32 v0, v23, v36
	v_mul_lo_u32 v23, v34, 12
	v_mul_lo_u32 v27, v32, 12
	v_sub_u32_e32 v23, v28, v23
	v_mul_lo_u32 v25, v34, s16
	v_lshlrev_b32_e32 v0, 4, v0
	v_sub_u32_e32 v27, v29, v27
	v_lshlrev_b32_e32 v23, 4, v23
	s_add_u32 s6, s6, 0x3000
	v_mul_lo_u32 v32, v32, s16
	v_add3_u32 v0, 0, v37, v0
	v_lshlrev_b32_e32 v27, 4, v27
	v_add3_u32 v23, 0, v25, v23
	s_addc_u32 s7, s7, 0
	v_add3_u32 v25, 0, v32, v27
	s_waitcnt vmcnt(4)
	ds_write_b128 v0, v[2:5]
	s_waitcnt vmcnt(3)
	ds_write_b128 v23, v[6:9]
	s_waitcnt vmcnt(2)
	ds_write_b128 v25, v[10:13]
	s_waitcnt vmcnt(1)
	ds_write_b128 v24, v[14:17] offset:13312
	s_waitcnt vmcnt(0)
	ds_write_b128 v26, v[18:21] offset:13312
	v_mov_b32_e32 v204, v0
	v_mov_b32_e32 v205, v23
	v_mov_b32_e32 v209, v25
	v_mov_b32_e32 v212, v24
	v_mov_b32_e32 v235, v26
	v_mov_b32_e32 v14, v1
	v_ashrrev_i32_e32 v23, 31, v22
	v_add_u32_e32 v2, 0x100, v22
	v_lshlrev_b32_e32 v0, 4, v22
	v_lshl_add_u64 v[4:5], v[22:23], 4, s[6:7]
	v_ashrrev_i32_e32 v3, 31, v2
	v_and_b32_e32 v0, 0x70, v0
	v_add_co_u32_e32 v6, vcc, s17, v4
	v_ashrrev_i32_e32 v10, 3, v22
	v_ashrrev_i32_e32 v11, 3, v2
	v_lshl_add_u64 v[2:3], v[2:3], 4, s[6:7]
	v_addc_co_u32_e32 v7, vcc, 0, v5, vcc
	v_lshl_add_u64 v[8:9], s[0:1], 0, v[0:1]
	global_load_dwordx4 v[168:171], v[4:5], off
	global_load_dwordx4 v[172:175], v[2:3], off
	v_mad_i64_i32 v[2:3], s[0:1], v10, s11, v[8:9]
	v_mad_i64_i32 v[4:5], s[0:1], v11, s11, v[8:9]
	global_load_dwordx4 v[176:179], v[6:7], off
	global_load_dwordx4 v[180:183], v[2:3], off offset:128
	global_load_dwordx4 v[184:187], v[4:5], off offset:128
	v_and_b32_e32 v2, 64, v200
	v_xor_b32_e32 v0, 32, v200
	v_add_u32_e32 v2, 64, v2
	v_cmp_lt_i32_e32 vcc, v0, v2
	v_readlane_b32 s0, v255, 23
	s_add_u32 s9, s0, s9
	v_cndmask_b32_e32 v0, v200, v0, vcc
	v_readlane_b32 s0, v255, 24
	v_lshlrev_b32_e32 v189, 2, v0
	v_sub_u32_e32 v0, v192, v190
	v_mul_u32_u24_e32 v2, 0x48, v30
	s_addc_u32 s10, s0, s10
	v_readlane_b32 s0, v255, 25
	v_mov_b32_e32 v15, v1
	v_lshl_add_u32 v214, v2, 1, v0
	s_add_u32 s0, s0, s13
	v_readlane_b32 s1, v255, 26
	v_mov_b32_e32 v0, v1
	v_mov_b32_e32 v2, v1
	v_mov_b32_e32 v3, v1
	v_mov_b32_e32 v4, v1
	v_mov_b32_e32 v5, v1
	v_mov_b32_e32 v6, v1
	v_mov_b32_e32 v7, v1
	v_mov_b32_e32 v8, v1
	v_mov_b32_e32 v9, v1
	v_mov_b32_e32 v10, v1
	v_mov_b32_e32 v11, v1
	v_mov_b32_e32 v12, v1
	v_mov_b32_e32 v13, v1
	v_mov_b64_e32 v[30:31], v[14:15]
	v_mov_b64_e32 v[46:47], v[14:15]
	v_mov_b64_e32 v[62:63], v[14:15]
	v_mov_b64_e32 v[78:79], v[14:15]
	s_movk_i32 s16, 0x2000
	s_mov_b32 s11, 0
	s_addc_u32 s1, s1, s12
	s_mov_b64 s[6:7], 0
	v_mov_b64_e32 v[28:29], v[12:13]
	v_mov_b64_e32 v[26:27], v[10:11]
	v_mov_b64_e32 v[24:25], v[8:9]
	v_mov_b64_e32 v[22:23], v[6:7]
	v_mov_b64_e32 v[20:21], v[4:5]
	v_mov_b64_e32 v[18:19], v[2:3]
	v_mov_b64_e32 v[16:17], v[0:1]
	v_mov_b64_e32 v[44:45], v[12:13]
	v_mov_b64_e32 v[42:43], v[10:11]
	v_mov_b64_e32 v[40:41], v[8:9]
	v_mov_b64_e32 v[38:39], v[6:7]
	v_mov_b64_e32 v[36:37], v[4:5]
	v_mov_b64_e32 v[34:35], v[2:3]
	v_mov_b64_e32 v[32:33], v[0:1]
	v_mov_b64_e32 v[60:61], v[12:13]
	v_mov_b64_e32 v[58:59], v[10:11]
	v_mov_b64_e32 v[56:57], v[8:9]
	v_mov_b64_e32 v[54:55], v[6:7]
	v_mov_b64_e32 v[52:53], v[4:5]
	v_mov_b64_e32 v[50:51], v[2:3]
	v_mov_b64_e32 v[48:49], v[0:1]
	v_mov_b64_e32 v[76:77], v[12:13]
	v_mov_b64_e32 v[74:75], v[10:11]
	v_mov_b64_e32 v[72:73], v[8:9]
	v_mov_b64_e32 v[70:71], v[6:7]
	v_mov_b64_e32 v[68:69], v[4:5]
	v_mov_b64_e32 v[66:67], v[2:3]
	v_mov_b64_e32 v[64:65], v[0:1]
	v_mov_b32_e32 v0, 0
	v_mov_b32_e32 v14, 0xf149f2ca
	s_waitcnt lgkmcnt(0)
	s_barrier
.LBB0_746:
	s_bitcmp1_b32 s11, 0
	s_cselect_b32 s12, 0x2c00, 0
	s_lshl_b32 s13, s12, 1
	v_add3_u32 v15, v192, s13, v191
	ds_read_b128 v[2:5], v15
	ds_read_b128 v[10:13], v194 offset:47104
	ds_read_b128 v[240:243], v15 offset:32
	ds_read_b128 v[216:219], v194 offset:47136
	ds_read_b128 v[244:247], v15 offset:64
	ds_read_b128 v[6:9], v194 offset:47168
	ds_read_b128 v[248:251], v15 offset:96
	ds_read_b128 v[220:223], v194 offset:47200
	s_waitcnt lgkmcnt(7)
	v_mfma_f32_32x32x16_bf16 v[112:127], v[2:5], v[144:147], 0
	s_waitcnt lgkmcnt(6)
	v_mfma_f32_32x32x16_bf16 v[96:111], v[2:5], v[10:13], 0
	ds_read_b128 v[2:5], v15 offset:128
	ds_read_b128 v[224:227], v194 offset:47232
	s_waitcnt lgkmcnt(7)
	v_mfma_f32_32x32x16_bf16 v[112:127], v[240:243], v[148:151], v[112:127]
	s_waitcnt lgkmcnt(6)
	v_mfma_f32_32x32x16_bf16 v[96:111], v[240:243], v[216:219], v[96:111]
	ds_read_b128 v[240:243], v15 offset:160
	ds_read_b128 v[228:231], v194 offset:47264
	s_waitcnt lgkmcnt(7)
	v_mfma_f32_32x32x16_bf16 v[112:127], v[244:247], v[152:155], v[112:127]
	s_waitcnt lgkmcnt(6)
	v_mfma_f32_32x32x16_bf16 v[96:111], v[244:247], v[6:9], v[96:111]
	ds_read_b128 v[244:247], v15 offset:6656
	s_waitcnt lgkmcnt(6)
	v_mfma_f32_32x32x16_bf16 v[112:127], v[248:251], v[156:159], v[112:127]
	s_waitcnt lgkmcnt(5)
	v_mfma_f32_32x32x16_bf16 v[96:111], v[248:251], v[220:223], v[96:111]
	ds_read_b128 v[248:251], v15 offset:6688
	s_waitcnt lgkmcnt(5)
	v_mfma_f32_32x32x16_bf16 v[112:127], v[2:5], v[160:163], v[112:127]
	s_waitcnt lgkmcnt(4)
	v_mfma_f32_32x32x16_bf16 v[96:111], v[2:5], v[224:227], v[96:111]
	ds_read_b128 v[2:5], v15 offset:6720
	s_waitcnt lgkmcnt(4)
	v_mfma_f32_32x32x16_bf16 v[112:127], v[240:243], v[164:167], v[112:127]
	s_waitcnt lgkmcnt(3)
	v_mfma_f32_32x32x16_bf16 v[96:111], v[240:243], v[228:231], v[96:111]
	ds_read_b128 v[240:243], v15 offset:6752
	s_waitcnt lgkmcnt(3)
	v_mfma_f32_32x32x16_bf16 v[128:143], v[244:247], v[144:147], 0
	v_mfma_f32_32x32x16_bf16 v[80:95], v[244:247], v[10:13], 0
	ds_read_b128 v[244:247], v15 offset:6784
	s_waitcnt lgkmcnt(3)
	v_mfma_f32_32x32x16_bf16 v[128:143], v[248:251], v[148:151], v[128:143]
	v_mfma_f32_32x32x16_bf16 v[80:95], v[248:251], v[216:219], v[80:95]
	ds_read_b128 v[248:251], v15 offset:6816
	s_waitcnt lgkmcnt(3)
	v_mfma_f32_32x32x16_bf16 v[128:143], v[2:5], v[152:155], v[128:143]
	v_mfma_f32_32x32x16_bf16 v[80:95], v[2:5], v[6:9], v[80:95]
	s_waitcnt lgkmcnt(2)
	v_mfma_f32_32x32x16_bf16 v[128:143], v[240:243], v[156:159], v[128:143]
	v_mfma_f32_32x32x16_bf16 v[80:95], v[240:243], v[220:223], v[80:95]
	s_waitcnt lgkmcnt(1)
	v_mfma_f32_32x32x16_bf16 v[128:143], v[244:247], v[160:163], v[128:143]
	v_mfma_f32_32x32x16_bf16 v[80:95], v[244:247], v[224:227], v[80:95]
	s_waitcnt lgkmcnt(0)
	v_mfma_f32_32x32x16_bf16 v[128:143], v[248:251], v[164:167], v[128:143]
	v_mfma_f32_32x32x16_bf16 v[80:95], v[248:251], v[228:231], v[80:95]
	v_max_f32_e32 v2, v113, v113
	v_max_f32_e32 v3, v112, v112
	v_max_f32_e32 v2, v3, v2
	v_max3_f32 v2, v2, v114, v115
	v_max3_f32 v2, v2, v116, v117
	v_max3_f32 v2, v2, v118, v119
	v_max3_f32 v2, v2, v120, v121
	v_max3_f32 v2, v2, v122, v123
	v_max3_f32 v2, v2, v124, v125
	v_max3_f32 v2, v2, v126, v127
	s_nop 0
	v_max3_f32 v2, v2, v128, v129
	v_max3_f32 v2, v2, v130, v131
	v_max3_f32 v2, v2, v132, v133
	v_max3_f32 v2, v2, v134, v135
	v_max3_f32 v2, v2, v136, v137
	v_max3_f32 v2, v2, v138, v139
	v_max3_f32 v2, v2, v140, v141
	v_max3_f32 v2, v2, v142, v143
	ds_bpermute_b32 v3, v189, v2
	s_waitcnt lgkmcnt(0)
	v_max_f32_e32 v3, v3, v3
	v_max_f32_e32 v2, v2, v3
	v_add_f32_e32 v3, 0xc1000000, v2
	v_cmp_gt_f32_e32 vcc, v3, v215
	s_cbranch_vccz .LBB0_748
	v_max_f32_e32 v2, v2, v2
	v_max_f32_e32 v3, v215, v215
	v_max_f32_e32 v3, v3, v2
	v_sub_f32_e32 v2, v215, v3
	v_exp_f32_e32 v2, v2
	v_mov_b32_e32 v215, v3
	v_mul_f32_e32 v0, v0, v2
	v_pk_mul_f32 v[78:79], v[78:79], v[2:3] op_sel_hi:[1,0]
	v_pk_mul_f32 v[76:77], v[76:77], v[2:3] op_sel_hi:[1,0]
	v_pk_mul_f32 v[74:75], v[74:75], v[2:3] op_sel_hi:[1,0]
	v_pk_mul_f32 v[72:73], v[72:73], v[2:3] op_sel_hi:[1,0]
	v_pk_mul_f32 v[70:71], v[70:71], v[2:3] op_sel_hi:[1,0]
	v_pk_mul_f32 v[68:69], v[68:69], v[2:3] op_sel_hi:[1,0]
	v_pk_mul_f32 v[66:67], v[66:67], v[2:3] op_sel_hi:[1,0]
	v_pk_mul_f32 v[64:65], v[64:65], v[2:3] op_sel_hi:[1,0]
	v_pk_mul_f32 v[62:63], v[62:63], v[2:3] op_sel_hi:[1,0]
	v_pk_mul_f32 v[60:61], v[60:61], v[2:3] op_sel_hi:[1,0]
	v_pk_mul_f32 v[58:59], v[58:59], v[2:3] op_sel_hi:[1,0]
	v_pk_mul_f32 v[56:57], v[56:57], v[2:3] op_sel_hi:[1,0]
	v_pk_mul_f32 v[54:55], v[54:55], v[2:3] op_sel_hi:[1,0]
	v_pk_mul_f32 v[52:53], v[52:53], v[2:3] op_sel_hi:[1,0]
	v_pk_mul_f32 v[50:51], v[50:51], v[2:3] op_sel_hi:[1,0]
	v_pk_mul_f32 v[48:49], v[48:49], v[2:3] op_sel_hi:[1,0]
.LBB0_748:
	v_sub_f32_e32 v2, v112, v215
	v_sub_f32_e32 v3, v113, v215
	v_sub_f32_e32 v4, v114, v215
	v_sub_f32_e32 v5, v115, v215
	v_sub_f32_e32 v6, v116, v215
	v_sub_f32_e32 v7, v117, v215
	v_sub_f32_e32 v8, v118, v215
	v_sub_f32_e32 v9, v119, v215
	v_exp_f32_e32 v15, v2
	v_exp_f32_e32 v216, v3
	v_exp_f32_e32 v217, v4
	v_exp_f32_e32 v218, v5
	v_exp_f32_e32 v219, v6
	v_exp_f32_e32 v220, v7
	v_exp_f32_e32 v221, v8
	v_exp_f32_e32 v222, v9
	v_sub_f32_e32 v2, v120, v215
	v_sub_f32_e32 v3, v121, v215
	v_sub_f32_e32 v4, v122, v215
	v_sub_f32_e32 v5, v123, v215
	v_sub_f32_e32 v6, v124, v215
	v_sub_f32_e32 v7, v125, v215
	v_sub_f32_e32 v8, v126, v215
	v_sub_f32_e32 v9, v127, v215
	v_exp_f32_e32 v223, v2
	v_exp_f32_e32 v224, v3
	v_exp_f32_e32 v225, v4
	v_exp_f32_e32 v226, v5
	v_exp_f32_e32 v227, v6
	v_exp_f32_e32 v228, v7
	v_exp_f32_e32 v229, v8
	v_exp_f32_e32 v230, v9
	v_sub_f32_e32 v2, v128, v215
	v_sub_f32_e32 v3, v129, v215
	v_sub_f32_e32 v4, v130, v215
	v_sub_f32_e32 v5, v131, v215
	v_sub_f32_e32 v6, v132, v215
	v_sub_f32_e32 v7, v133, v215
	v_sub_f32_e32 v8, v134, v215
	v_sub_f32_e32 v9, v135, v215
	v_exp_f32_e32 v231, v2
	v_exp_f32_e32 v232, v3
	v_exp_f32_e32 v233, v4
	v_exp_f32_e32 v234, v5
	v_exp_f32_e32 v132, v6
	v_exp_f32_e32 v133, v7
	v_exp_f32_e32 v134, v8
	v_exp_f32_e32 v135, v9
	v_sub_f32_e32 v2, v136, v215
	v_sub_f32_e32 v3, v137, v215
	v_sub_f32_e32 v4, v138, v215
	v_sub_f32_e32 v5, v139, v215
	v_sub_f32_e32 v6, v140, v215
	v_sub_f32_e32 v7, v141, v215
	v_sub_f32_e32 v8, v142, v215
	v_sub_f32_e32 v9, v143, v215
	v_exp_f32_e32 v136, v2
	v_exp_f32_e32 v137, v3
	v_exp_f32_e32 v138, v4
	v_exp_f32_e32 v139, v5
	v_exp_f32_e32 v140, v6
	v_exp_f32_e32 v141, v7
	v_exp_f32_e32 v142, v8
	v_exp_f32_e32 v143, v9
	v_lshl_add_u32 v10, s12, 1, v214
	v_add_u32_e32 v128, 0x3000, v10
	v_add_u32_e32 v129, 0x4000, v10
	ds_read2_b64 v[6:9], v128 offset0:128 offset1:130
	ds_read2_b64 v[2:5], v128 offset0:132 offset1:134
	ds_read2_b64 v[10:13], v129 offset0:192 offset1:194
	v_cvt_pk_bf16_f32 v112, v15, v216
	v_cvt_pk_bf16_f32 v113, v217, v218
	v_cvt_pk_bf16_f32 v114, v219, v220
	v_cvt_pk_bf16_f32 v115, v221, v222
	v_cvt_pk_bf16_f32 v116, v223, v224
	v_cvt_pk_bf16_f32 v117, v225, v226
	s_waitcnt lgkmcnt(2)
	v_mfma_f32_32x32x16_bf16 v[64:79], v[6:9], v[112:115], v[64:79]
	v_cvt_pk_bf16_f32 v118, v227, v228
	v_cvt_pk_bf16_f32 v119, v229, v230
	ds_read2_b64 v[120:123], v129 offset0:200 offset1:202
	v_max_f32_e32 v202, v97, v97
	v_max_f32_e32 v203, v96, v96
	v_max_f32_e32 v202, v203, v202
	v_max3_f32 v202, v202, v98, v99
	s_waitcnt lgkmcnt(1)
	v_mfma_f32_32x32x16_bf16 v[48:63], v[10:13], v[112:115], v[48:63]
	ds_read2_b64 v[112:115], v129 offset0:196 offset1:198
	v_max3_f32 v202, v202, v100, v101
	v_max3_f32 v202, v202, v102, v103
	v_max3_f32 v202, v202, v104, v105
	v_max3_f32 v202, v202, v106, v107
	v_cvt_pk_bf16_f32 v124, v231, v232
	v_cvt_pk_bf16_f32 v125, v233, v234
	v_mfma_f32_32x32x16_bf16 v[64:79], v[2:5], v[116:119], v[64:79]
	v_cvt_pk_bf16_f32 v126, v132, v133
	v_cvt_pk_bf16_f32 v127, v134, v135
	v_max3_f32 v202, v202, v108, v109
	v_max3_f32 v202, v202, v110, v111
	v_max3_f32 v202, v202, v80, v81
	v_max3_f32 v202, v202, v82, v83
	v_max3_f32 v202, v202, v84, v85
	s_waitcnt lgkmcnt(0)
	v_mfma_f32_32x32x16_bf16 v[48:63], v[112:115], v[116:119], v[48:63]
	ds_read2_b64 v[116:119], v128 offset0:136 offset1:138
	v_max3_f32 v202, v202, v86, v87
	v_max3_f32 v202, v202, v88, v89
	v_max3_f32 v202, v202, v90, v91
	v_max3_f32 v202, v202, v92, v93
	v_cvt_pk_bf16_f32 v236, v136, v137
	v_cvt_pk_bf16_f32 v237, v138, v139
	s_waitcnt lgkmcnt(0)
	v_mfma_f32_32x32x16_bf16 v[64:79], v[116:119], v[124:127], v[64:79]
	v_cvt_pk_bf16_f32 v238, v140, v141
	v_cvt_pk_bf16_f32 v239, v142, v143
	v_max3_f32 v202, v202, v94, v95
	ds_bpermute_b32 v203, v189, v202
	s_waitcnt lgkmcnt(0)
	v_max_f32_e32 v203, v203, v203
	v_mfma_f32_32x32x16_bf16 v[48:63], v[120:123], v[124:127], v[48:63]
	ds_read2_b64 v[124:127], v128 offset0:140 offset1:142
	ds_read2_b64 v[128:131], v129 offset0:204 offset1:206
	v_max_f32_e32 v208, v202, v203
	v_add_f32_e32 v203, 0xc1000000, v208
	v_cmp_gt_f32_e32 vcc, v203, v14
	s_waitcnt lgkmcnt(1)
	v_mfma_f32_32x32x16_bf16 v[64:79], v[124:127], v[236:239], v[64:79]
	s_waitcnt lgkmcnt(0)
	v_mfma_f32_32x32x16_bf16 v[48:63], v[128:131], v[236:239], v[48:63]
	s_cbranch_vccz .LBB0_750
	v_max_f32_e32 v202, v208, v208
	v_max_f32_e32 v203, v14, v14
	v_max_f32_e32 v202, v203, v202
	v_sub_f32_e32 v14, v14, v202
	v_exp_f32_e32 v14, v14
	s_nop 0
	v_mul_f32_e32 v195, v195, v14
	v_pk_mul_f32 v[46:47], v[46:47], v[14:15] op_sel_hi:[1,0]
	v_pk_mul_f32 v[44:45], v[44:45], v[14:15] op_sel_hi:[1,0]
	v_pk_mul_f32 v[42:43], v[42:43], v[14:15] op_sel_hi:[1,0]
	v_pk_mul_f32 v[40:41], v[40:41], v[14:15] op_sel_hi:[1,0]
	v_pk_mul_f32 v[38:39], v[38:39], v[14:15] op_sel_hi:[1,0]
	v_pk_mul_f32 v[36:37], v[36:37], v[14:15] op_sel_hi:[1,0]
	v_pk_mul_f32 v[34:35], v[34:35], v[14:15] op_sel_hi:[1,0]
	v_pk_mul_f32 v[32:33], v[32:33], v[14:15] op_sel_hi:[1,0]
	v_pk_mul_f32 v[30:31], v[30:31], v[14:15] op_sel_hi:[1,0]
	v_pk_mul_f32 v[28:29], v[28:29], v[14:15] op_sel_hi:[1,0]
	v_pk_mul_f32 v[26:27], v[26:27], v[14:15] op_sel_hi:[1,0]
	v_pk_mul_f32 v[24:25], v[24:25], v[14:15] op_sel_hi:[1,0]
	v_pk_mul_f32 v[22:23], v[22:23], v[14:15] op_sel_hi:[1,0]
	v_pk_mul_f32 v[20:21], v[20:21], v[14:15] op_sel_hi:[1,0]
	v_pk_mul_f32 v[18:19], v[18:19], v[14:15] op_sel_hi:[1,0]
	v_pk_mul_f32 v[16:17], v[16:17], v[14:15] op_sel_hi:[1,0]
	v_mov_b32_e32 v14, v202
.LBB0_750:
	v_sub_f32_e32 v96, v96, v14
	v_sub_f32_e32 v97, v97, v14
	v_sub_f32_e32 v98, v98, v14
	v_sub_f32_e32 v99, v99, v14
	v_sub_f32_e32 v100, v100, v14
	v_sub_f32_e32 v101, v101, v14
	v_sub_f32_e32 v102, v102, v14
	v_sub_f32_e32 v103, v103, v14
	v_exp_f32_e32 v96, v96
	v_exp_f32_e32 v97, v97
	v_exp_f32_e32 v98, v98
	v_exp_f32_e32 v99, v99
	v_exp_f32_e32 v100, v100
	v_exp_f32_e32 v101, v101
	v_exp_f32_e32 v102, v102
	v_exp_f32_e32 v103, v103
	v_cvt_pk_bf16_f32 v236, v96, v97
	v_cvt_pk_bf16_f32 v237, v98, v99
	v_cvt_pk_bf16_f32 v238, v100, v101
	v_cvt_pk_bf16_f32 v239, v102, v103
	v_sub_f32_e32 v104, v104, v14
	v_sub_f32_e32 v105, v105, v14
	v_mfma_f32_32x32x16_bf16 v[32:47], v[6:9], v[236:239], v[32:47]
	v_sub_f32_e32 v106, v106, v14
	v_sub_f32_e32 v107, v107, v14
	v_sub_f32_e32 v108, v108, v14
	v_sub_f32_e32 v109, v109, v14
	v_sub_f32_e32 v110, v110, v14
	v_sub_f32_e32 v111, v111, v14
	v_exp_f32_e32 v104, v104
	v_mfma_f32_32x32x16_bf16 v[16:31], v[10:13], v[236:239], v[16:31]
	v_exp_f32_e32 v105, v105
	v_exp_f32_e32 v106, v106
	v_exp_f32_e32 v107, v107
	v_exp_f32_e32 v108, v108
	v_exp_f32_e32 v109, v109
	v_exp_f32_e32 v110, v110
	v_exp_f32_e32 v111, v111
	v_sub_f32_e32 v7, v82, v14
	v_sub_f32_e32 v8, v83, v14
	v_sub_f32_e32 v9, v84, v14
	v_sub_f32_e32 v10, v85, v14
	v_cvt_pk_bf16_f32 v82, v104, v105
	v_cvt_pk_bf16_f32 v83, v106, v107
	v_cvt_pk_bf16_f32 v84, v108, v109
	v_cvt_pk_bf16_f32 v85, v110, v111
	v_sub_f32_e32 v80, v80, v14
	v_sub_f32_e32 v6, v81, v14
	v_mfma_f32_32x32x16_bf16 v[32:47], v[2:5], v[82:85], v[32:47]
	v_sub_f32_e32 v2, v86, v14
	v_sub_f32_e32 v3, v87, v14
	v_exp_f32_e32 v80, v80
	v_exp_f32_e32 v6, v6
	v_exp_f32_e32 v7, v7
	v_exp_f32_e32 v8, v8
	v_exp_f32_e32 v9, v9
	v_mfma_f32_32x32x16_bf16 v[16:31], v[112:115], v[82:85], v[16:31]
	v_exp_f32_e32 v10, v10
	v_exp_f32_e32 v2, v2
	v_exp_f32_e32 v3, v3
	v_cvt_pk_bf16_f32 v82, v80, v6
	v_cvt_pk_bf16_f32 v83, v7, v8
	v_cvt_pk_bf16_f32 v84, v9, v10
	v_cvt_pk_bf16_f32 v85, v2, v3
	v_sub_f32_e32 v4, v88, v14
	v_sub_f32_e32 v5, v89, v14
	v_mfma_f32_32x32x16_bf16 v[32:47], v[116:119], v[82:85], v[32:47]
	v_sub_f32_e32 v11, v90, v14
	v_sub_f32_e32 v12, v91, v14
	v_sub_f32_e32 v13, v92, v14
	v_sub_f32_e32 v81, v93, v14
	v_sub_f32_e32 v86, v94, v14
	v_exp_f32_e32 v4, v4
	v_exp_f32_e32 v5, v5
	v_mfma_f32_32x32x16_bf16 v[16:31], v[120:123], v[82:85], v[16:31]
	v_sub_f32_e32 v83, v95, v14
	v_exp_f32_e32 v11, v11
	v_exp_f32_e32 v12, v12
	v_exp_f32_e32 v13, v13
	v_exp_f32_e32 v81, v81
	v_exp_f32_e32 v82, v86
	v_exp_f32_e32 v83, v83
	v_cvt_pk_bf16_f32 v84, v4, v5
	v_cvt_pk_bf16_f32 v85, v11, v12
	v_cvt_pk_bf16_f32 v86, v13, v81
	v_cvt_pk_bf16_f32 v87, v82, v83
	s_add_i32 s12, s11, 1
	s_cmp_gt_u32 s11, 34
	v_mfma_f32_32x32x16_bf16 v[32:47], v[124:127], v[84:87], v[32:47]
	s_movk_i32 s14, 0xd0
	v_mfma_f32_32x32x16_bf16 v[16:31], v[128:131], v[84:87], v[16:31]
	s_cbranch_scc1 .LBB0_753
	s_bitcmp1_b32 s12, 0
	s_cselect_b32 s11, 0x5800, 0
	v_add_u32_e32 v84, s11, v204
	v_add_u32_e32 v85, s11, v205
	v_add_u32_e32 v86, s11, v209
	v_add_u32_e32 v87, s11, v212
	v_add_u32_e32 v88, s11, v235
	s_waitcnt vmcnt(4)
	ds_write_b128 v84, v[168:171]
	s_waitcnt vmcnt(3)
	ds_write_b128 v85, v[172:175]
	s_waitcnt vmcnt(2)
	ds_write_b128 v86, v[176:179]
	s_waitcnt vmcnt(1)
	ds_write_b128 v87, v[180:183] offset:13312
	s_waitcnt vmcnt(0)
	ds_write_b128 v88, v[184:187] offset:13312
	s_cmp_eq_u32 s6, 0x66000
	s_cbranch_scc1 .LBB0_753
	v_mov_b32_e32 v84, v193
	s_add_u32 s14, s9, s6
	s_addc_u32 s15, s10, s7
	v_ashrrev_i32_e32 v85, 31, v84
	v_add_u32_e32 v88, 0x100, v84
	v_lshl_add_u64 v[86:87], v[84:85], 4, s[14:15]
	v_ashrrev_i32_e32 v89, 31, v88
	v_lshl_add_u64 v[90:91], v[88:89], 4, s[14:15]
	global_load_dwordx4 v[168:171], v[86:87], off
	global_load_dwordx4 v[172:175], v[90:91], off
	v_add_co_u32_e32 v86, vcc, s16, v86
	v_ashrrev_i32_e32 v85, 3, v84
	s_nop 0
	v_addc_co_u32_e32 v87, vcc, 0, v87, vcc
	s_movk_i32 s11, 0x1200
	v_lshlrev_b32_e32 v84, 4, v84
	global_load_dwordx4 v[176:179], v[86:87], off
	v_mad_i64_i32 v[86:87], s[14:15], v85, s11, 0
	v_and_b32_e32 v89, 0x70, v84
	v_or_b32_e32 v86, v86, v89
	v_lshl_add_u64 v[84:85], s[0:1], 0, v[86:87]
	v_ashrrev_i32_e32 v86, 3, v88
	v_mad_i64_i32 v[86:87], s[14:15], v86, s11, 0
	v_or_b32_e32 v86, v86, v89
	v_lshl_add_u64 v[86:87], s[0:1], 0, v[86:87]
	global_load_dwordx4 v[180:183], v[84:85], off
	global_load_dwordx4 v[184:187], v[86:87], off
.LBB0_753:
	v_add_f32_e32 v84, 0, v96
	v_add_f32_e32 v85, 0, v15
	s_add_u32 s6, s6, 0x3000
	v_add_f32_e32 v84, v97, v84
	v_add_f32_e32 v85, v216, v85
	s_addc_u32 s7, s7, 0
	v_add_f32_e32 v84, v98, v84
	v_add_f32_e32 v85, v217, v85
	s_add_u32 s0, s0, 0x80
	v_add_f32_e32 v84, v99, v84
	v_add_f32_e32 v85, v218, v85
	s_addc_u32 s1, s1, 0
	v_add_f32_e32 v84, v100, v84
	v_add_f32_e32 v85, v219, v85
	v_add_f32_e32 v84, v101, v84
	v_add_f32_e32 v85, v220, v85
	v_add_f32_e32 v84, v102, v84
	v_add_f32_e32 v85, v221, v85
	v_add_f32_e32 v84, v103, v84
	v_add_f32_e32 v85, v222, v85
	v_add_f32_e32 v84, v104, v84
	v_add_f32_e32 v85, v223, v85
	v_add_f32_e32 v84, v105, v84
	v_add_f32_e32 v85, v224, v85
	v_add_f32_e32 v84, v106, v84
	v_add_f32_e32 v85, v225, v85
	v_add_f32_e32 v84, v107, v84
	v_add_f32_e32 v85, v226, v85
	v_add_f32_e32 v84, v108, v84
	v_add_f32_e32 v85, v227, v85
	v_add_f32_e32 v84, v109, v84
	v_add_f32_e32 v85, v228, v85
	v_add_f32_e32 v84, v110, v84
	v_add_f32_e32 v85, v229, v85
	v_add_f32_e32 v84, v111, v84
	v_add_f32_e32 v85, v230, v85
	v_add_f32_e32 v80, v80, v84
	v_add_f32_e32 v85, v231, v85
	v_add_f32_e32 v6, v6, v80
	v_add_f32_e32 v85, v232, v85
	v_add_f32_e32 v6, v7, v6
	v_add_f32_e32 v85, v233, v85
	v_add_f32_e32 v6, v8, v6
	v_add_f32_e32 v85, v234, v85
	v_add_f32_e32 v6, v9, v6
	v_add_f32_e32 v85, v132, v85
	v_add_f32_e32 v6, v10, v6
	v_add_f32_e32 v85, v133, v85
	v_add_f32_e32 v2, v2, v6
	v_add_f32_e32 v85, v134, v85
	v_add_f32_e32 v2, v3, v2
	v_add_f32_e32 v85, v135, v85
	v_add_f32_e32 v2, v4, v2
	v_add_f32_e32 v85, v136, v85
	v_add_f32_e32 v2, v5, v2
	v_add_f32_e32 v85, v137, v85
	v_add_f32_e32 v2, v11, v2
	v_add_f32_e32 v85, v138, v85
	v_add_f32_e32 v2, v12, v2
	v_add_f32_e32 v85, v139, v85
	v_add_f32_e32 v2, v13, v2
	v_add_f32_e32 v85, v140, v85
	v_add_f32_e32 v2, v81, v2
	v_add_f32_e32 v85, v141, v85
	v_add_f32_e32 v2, v82, v2
	v_add_f32_e32 v85, v142, v85
	v_add_f32_e32 v2, v83, v2
	v_add_f32_e32 v85, v143, v85
	v_add_f32_e32 v195, v195, v2
	v_add_f32_e32 v0, v0, v85
	s_cmp_lg_u32 s6, 0x6c000
	s_waitcnt lgkmcnt(0)
	s_barrier
	s_cbranch_scc0 .LBB0_738
	s_mov_b32 s11, s12
	s_branch .LBB0_746
